# differential-attention tile loop hand-rewritten: software-pipelined two-phase schedule (S(t+1)/PV(t) MFMAs interleaved with exp/rowsum/cvt of the other component), in-place exp and bf16 pack, 4-slot L
# speedup vs baseline: 1.0397x; 1.0385x over previous
.LBB0_574:
	s_add_i32 s11, s11, s17
	v_lshlrev_b32_e32 v182, 2, v0
	v_lshrrev_b32_e32 v3, 2, v1
	s_mul_hi_u32 s13, s11, 0x1200
	s_mulk_i32 s11, 0x1200
	v_readlane_b32 s16, v252, 52
	v_and_or_b32 v3, v3, 3, v182
	v_readlane_b32 s17, v252, 53
	s_add_u32 s12, s16, s11
	v_lshlrev_b32_e32 v4, 1, v1
	v_lshlrev_b32_e32 v184, 6, v3
	s_addc_u32 s13, s17, s13
	v_add_u32_e32 v3, 0x4000, v183
	v_and_b32_e32 v185, 32, v4
	v_lshl_add_u64 v[4:5], v[126:127], 1, s[12:13]
	s_mov_b64 s[16:17], 0xe00
	v_readfirstlane_b32 s11, v3
	v_add_u32_e32 v3, 0x6000, v183
	v_lshl_add_u64 v[4:5], v[4:5], 0, s[16:17]
	s_mov_b32 m0, s11
	v_readfirstlane_b32 s11, v3
	global_load_lds_dwordx4 v[4:5], off
	v_lshl_add_u64 v[4:5], v[124:125], 1, s[12:13]
	s_mov_b32 m0, s11
	v_lshlrev_b32_e32 v186, 7, v2
	global_load_lds_dwordx4 v[4:5], off
	v_lshrrev_b32_e32 v2, 1, v1
	v_bfe_u32 v1, v1, 1, 3
	v_bitop3_b32 v2, v0, v2, 7 bitop3:0x78
	v_lshlrev_b32_e32 v187, 4, v2
	v_bitop3_b32 v2, v0, v1, 2 bitop3:0x36
	s_waitcnt vmcnt(2)
	s_barrier
	v_lshlrev_b32_e32 v188, 4, v2
	v_bitop3_b32 v2, v0, v1, 4 bitop3:0x36
	v_bitop3_b32 v0, v0, v1, 6 bitop3:0x36
	v_lshlrev_b32_e32 v190, 4, v0
	v_mov_b32_e32 v0, 0
	v_ashrrev_i32_e32 v123, 31, v122
	s_or_b32 s9, s9, 0x2080
	s_or_b32 s16, s10, 0x80
	v_lshlrev_b32_e32 v189, 4, v2
	s_lshl_b32 s17, s15, 6
	s_mov_b32 s18, 0
	v_mov_b32_e32 v1, v0
	v_mov_b32_e32 v2, v0
	v_mov_b32_e32 v3, v0
	v_mov_b32_e32 v4, v0
	v_mov_b32_e32 v5, v0
	v_mov_b32_e32 v6, v0
	v_mov_b32_e32 v7, v0
	v_mov_b32_e32 v8, v0
	v_mov_b32_e32 v9, v0
	v_mov_b32_e32 v10, v0
	v_mov_b32_e32 v11, v0
	v_mov_b32_e32 v12, v0
	v_mov_b32_e32 v13, v0
	v_mov_b32_e32 v14, v0
	v_mov_b32_e32 v15, v0
	v_mov_b32_e32 v32, v0
	v_mov_b32_e32 v33, v0
	v_mov_b32_e32 v34, v0
	v_mov_b32_e32 v35, v0
	v_mov_b32_e32 v36, v0
	v_mov_b32_e32 v37, v0
	v_mov_b32_e32 v38, v0
	v_mov_b32_e32 v39, v0
	v_mov_b32_e32 v40, v0
	v_mov_b32_e32 v41, v0
	v_mov_b32_e32 v42, v0
	v_mov_b32_e32 v43, v0
	v_mov_b32_e32 v44, v0
	v_mov_b32_e32 v45, v0
	v_mov_b32_e32 v46, v0
	v_mov_b32_e32 v47, v0
	v_mov_b32_e32 v16, v0
	v_mov_b32_e32 v17, v0
	v_mov_b32_e32 v18, v0
	v_mov_b32_e32 v19, v0
	v_mov_b32_e32 v20, v0
	v_mov_b32_e32 v21, v0
	v_mov_b32_e32 v22, v0
	v_mov_b32_e32 v23, v0
	v_mov_b32_e32 v24, v0
	v_mov_b32_e32 v25, v0
	v_mov_b32_e32 v26, v0
	v_mov_b32_e32 v27, v0
	v_mov_b32_e32 v28, v0
	v_mov_b32_e32 v29, v0
	v_mov_b32_e32 v30, v0
	v_mov_b32_e32 v31, v0
	v_mov_b32_e32 v48, v0
	v_mov_b32_e32 v49, v0
	v_mov_b32_e32 v50, v0
	v_mov_b32_e32 v51, v0
	v_mov_b32_e32 v52, v0
	v_mov_b32_e32 v53, v0
	v_mov_b32_e32 v54, v0
	v_mov_b32_e32 v55, v0
	v_mov_b32_e32 v56, v0
	v_mov_b32_e32 v57, v0
	v_mov_b32_e32 v58, v0
	v_mov_b32_e32 v59, v0
	v_mov_b32_e32 v60, v0
	v_mov_b32_e32 v61, v0
	v_mov_b32_e32 v62, v0
	v_mov_b32_e32 v63, v0
	v_mov_b32_e32 v128, v0
	v_mov_b32_e32 v129, v0
	s_waitcnt vmcnt(0)
	v_add_u32_e32 v200, v186, v187
	v_add_u32_e32 v201, v186, v188
	v_add_u32_e32 v202, v186, v189
	v_add_u32_e32 v203, v186, v190
	v_add3_u32 v204, v184, v160, v185
	v_readfirstlane_b32 s18, v183
	v_readlane_b32 s22, v252, 52
	v_readlane_b32 s23, v252, 53
	v_mov_b32_e32 v130, 0
	v_mov_b32_e32 v131, 0
	s_mov_b64 s[12:13], 0xe00
	v_lshl_add_u64 v[206:207], v[126:127], 1, s[22:23]
	v_lshl_add_u64 v[210:211], v[124:125], 1, s[22:23]
	v_lshl_add_u64 v[206:207], v[206:207], 0, s[12:13]
	s_cmpk_lt_u32 s15, 0x7e
	s_cselect_b32 s12, s16, s9
	s_add_i32 s12, s12, s17
	s_mul_i32 s12, s12, 0x1200
	s_mov_b32 s13, 0
	s_add_i32 s10, s18, 0x8000
	s_mov_b32 m0, s10
	v_lshl_add_u64 v[222:223], v[206:207], 0, s[12:13]
	global_load_lds_dwordx4 v[222:223], off
	s_add_i32 m0, s10, 0x2000
	v_lshl_add_u64 v[222:223], v[210:211], 0, s[12:13]
	global_load_lds_dwordx4 v[222:223], off
	ds_read_b128 v[112:115], v200
	ds_read_b128 v[116:119], v200 offset:4096
	ds_read_b128 v[148:151], v201
	ds_read_b128 v[152:155], v201 offset:4096
	ds_read_b128 v[156:159], v202
	ds_read_b128 v[162:165], v202 offset:4096
	ds_read_b128 v[174:177], v203
	ds_read_b128 v[178:181], v203 offset:4096
	s_waitcnt lgkmcnt(0)
	v_mfma_f32_32x32x16_bf16 v[64:79], v[112:115], v[80:83], 0
	v_mfma_f32_32x32x16_bf16 v[96:111], v[116:119], v[80:83], 0
	v_mfma_f32_32x32x16_bf16 v[64:79], v[148:151], v[84:87], v[64:79]
	v_mfma_f32_32x32x16_bf16 v[96:111], v[152:155], v[84:87], v[96:111]
	v_mfma_f32_32x32x16_bf16 v[132:147], v[156:159], v[88:91], 0
	v_mfma_f32_32x32x16_bf16 v[184:199], v[162:165], v[88:91], 0
	v_mfma_f32_32x32x16_bf16 v[132:147], v[174:177], v[92:95], v[132:147]
	v_mfma_f32_32x32x16_bf16 v[184:199], v[178:181], v[92:95], v[184:199]
	s_nop 7
	v_exp_f32_e32 v64, v64
	v_exp_f32_e32 v65, v65
	v_exp_f32_e32 v66, v66
	v_exp_f32_e32 v67, v67
	v_exp_f32_e32 v68, v68
	v_exp_f32_e32 v69, v69
	v_exp_f32_e32 v70, v70
	v_exp_f32_e32 v71, v71
	v_exp_f32_e32 v72, v72
	v_exp_f32_e32 v73, v73
	v_exp_f32_e32 v74, v74
	v_exp_f32_e32 v75, v75
	v_exp_f32_e32 v76, v76
	v_exp_f32_e32 v77, v77
	v_exp_f32_e32 v78, v78
	v_exp_f32_e32 v79, v79
	v_add_f32_e32 v128, v64, v128
	v_add_f32_e32 v130, v65, v130
	v_add_f32_e32 v128, v66, v128
	v_add_f32_e32 v130, v67, v130
	v_add_f32_e32 v128, v68, v128
	v_add_f32_e32 v130, v69, v130
	v_add_f32_e32 v128, v70, v128
	v_add_f32_e32 v130, v71, v130
	v_add_f32_e32 v128, v72, v128
	v_add_f32_e32 v130, v73, v130
	v_add_f32_e32 v128, v74, v128
	v_add_f32_e32 v130, v75, v130
	v_add_f32_e32 v128, v76, v128
	v_add_f32_e32 v130, v77, v130
	v_add_f32_e32 v128, v78, v128
	v_add_f32_e32 v130, v79, v130
	v_cvt_pk_bf16_f32 v64, v64, v65
	v_cvt_pk_bf16_f32 v65, v66, v67
	v_cvt_pk_bf16_f32 v66, v68, v69
	v_cvt_pk_bf16_f32 v67, v70, v71
	v_cvt_pk_bf16_f32 v68, v72, v73
	v_cvt_pk_bf16_f32 v69, v74, v75
	v_cvt_pk_bf16_f32 v70, v76, v77
	v_cvt_pk_bf16_f32 v71, v78, v79
	v_exp_f32_e32 v96, v96
	v_exp_f32_e32 v97, v97
	v_exp_f32_e32 v98, v98
	v_exp_f32_e32 v99, v99
	v_exp_f32_e32 v100, v100
	v_exp_f32_e32 v101, v101
	v_exp_f32_e32 v102, v102
	v_exp_f32_e32 v103, v103
	v_exp_f32_e32 v104, v104
	v_exp_f32_e32 v105, v105
	v_exp_f32_e32 v106, v106
	v_exp_f32_e32 v107, v107
	v_exp_f32_e32 v108, v108
	v_exp_f32_e32 v109, v109
	v_exp_f32_e32 v110, v110
	v_exp_f32_e32 v111, v111
	v_add_f32_e32 v128, v96, v128
	v_add_f32_e32 v130, v97, v130
	v_add_f32_e32 v128, v98, v128
	v_add_f32_e32 v130, v99, v130
	v_add_f32_e32 v128, v100, v128
	v_add_f32_e32 v130, v101, v130
	v_add_f32_e32 v128, v102, v128
	v_add_f32_e32 v130, v103, v130
	v_add_f32_e32 v128, v104, v128
	v_add_f32_e32 v130, v105, v130
	v_add_f32_e32 v128, v106, v128
	v_add_f32_e32 v130, v107, v130
	v_add_f32_e32 v128, v108, v128
	v_add_f32_e32 v130, v109, v130
	v_add_f32_e32 v128, v110, v128
	v_add_f32_e32 v130, v111, v130
	v_cvt_pk_bf16_f32 v96, v96, v97
	v_cvt_pk_bf16_f32 v97, v98, v99
	v_cvt_pk_bf16_f32 v98, v100, v101
	v_cvt_pk_bf16_f32 v99, v102, v103
	v_cvt_pk_bf16_f32 v100, v104, v105
	v_cvt_pk_bf16_f32 v101, v106, v107
	v_cvt_pk_bf16_f32 v102, v108, v109
	v_cvt_pk_bf16_f32 v103, v110, v111
	s_barrier
.Ldiff_loop:
	s_cmpk_lt_u32 s15, 0x81
	s_cbranch_scc0 .Ldiff_nodma
	s_cmpk_lt_u32 s15, 0x7d
	s_cselect_b32 s12, s16, s9
	s_add_i32 s12, s12, s17
	s_add_i32 s12, s12, 64
	s_mul_i32 s12, s12, 0x1200
	s_mov_b32 s13, 0
	s_add_i32 s10, s15, 3
	s_and_b32 s10, s10, 3
	s_lshl_b32 s10, s10, 14
	s_add_i32 s10, s10, s18
	s_mov_b32 m0, s10
	v_lshl_add_u64 v[222:223], v[206:207], 0, s[12:13]
	global_load_lds_dwordx4 v[222:223], off
	s_add_i32 m0, s10, 0x2000
	v_lshl_add_u64 v[222:223], v[210:211], 0, s[12:13]
	global_load_lds_dwordx4 v[222:223], off
.Ldiff_nodma:
	s_and_b32 s19, s15, 3
	s_lshl_b32 s19, s19, 14
	s_add_i32 s20, s15, 1
	s_and_b32 s20, s20, 3
	s_lshl_b32 s20, s20, 14
	v_add_u32_e32 v221, s19, v204
	v_add_u32_e32 v219, s20, v200
	v_add_u32_e32 v220, s20, v201
	ds_read_b64_tr_b16 v[156:157], v221 offset:8192
	ds_read_b64_tr_b16 v[158:159], v221 offset:9216
	ds_read_b64_tr_b16 v[162:163], v221 offset:8704
	ds_read_b64_tr_b16 v[164:165], v221 offset:9728
	ds_read_b64_tr_b16 v[174:175], v221 offset:10240
	ds_read_b64_tr_b16 v[176:177], v221 offset:11264
	ds_read_b128 v[112:115], v219
	ds_read_b128 v[116:119], v219 offset:4096
	ds_read_b128 v[148:151], v220
	ds_read_b128 v[152:155], v220 offset:4096
	v_exp_f32_e32 v132, v132
	v_exp_f32_e32 v133, v133
	v_exp_f32_e32 v134, v134
	v_exp_f32_e32 v135, v135
	s_waitcnt lgkmcnt(8)
	v_mfma_f32_32x32x16_bf16 v[32:47], v[156:159], v[64:67], v[32:47]
	ds_read_b64_tr_b16 v[178:179], v221 offset:10752
	ds_read_b64_tr_b16 v[180:181], v221 offset:11776
	v_exp_f32_e32 v136, v136
	v_exp_f32_e32 v137, v137
	v_exp_f32_e32 v138, v138
	v_exp_f32_e32 v139, v139
	v_exp_f32_e32 v140, v140
	v_exp_f32_e32 v141, v141
	v_exp_f32_e32 v142, v142
	s_waitcnt lgkmcnt(8)
	v_mfma_f32_32x32x16_bf16 v[0:15], v[162:165], v[64:67], v[0:15]
	ds_read_b64_tr_b16 v[156:157], v221 offset:12288
	ds_read_b64_tr_b16 v[158:159], v221 offset:13312
	v_exp_f32_e32 v143, v143
	v_exp_f32_e32 v144, v144
	v_exp_f32_e32 v145, v145
	v_exp_f32_e32 v146, v146
	v_exp_f32_e32 v147, v147
	v_add_f32_e32 v129, v132, v129
	s_waitcnt lgkmcnt(8)
	v_mfma_f32_32x32x16_bf16 v[32:47], v[174:177], v[68:71], v[32:47]
	ds_read_b64_tr_b16 v[162:163], v221 offset:12800
	ds_read_b64_tr_b16 v[164:165], v221 offset:13824
	v_add_f32_e32 v131, v133, v131
	v_add_f32_e32 v129, v134, v129
	v_add_f32_e32 v131, v135, v131
	v_add_f32_e32 v129, v136, v129
	v_add_f32_e32 v131, v137, v131
	v_add_f32_e32 v129, v138, v129
	v_add_f32_e32 v131, v139, v131
	s_waitcnt lgkmcnt(4)
	v_mfma_f32_32x32x16_bf16 v[0:15], v[178:181], v[68:71], v[0:15]
	ds_read_b64_tr_b16 v[174:175], v221 offset:14336
	ds_read_b64_tr_b16 v[176:177], v221 offset:15360
	v_add_f32_e32 v129, v140, v129
	v_add_f32_e32 v131, v141, v131
	v_add_f32_e32 v129, v142, v129
	v_add_f32_e32 v131, v143, v131
	v_add_f32_e32 v129, v144, v129
	v_add_f32_e32 v131, v145, v131
	s_waitcnt lgkmcnt(4)
	v_mfma_f32_32x32x16_bf16 v[32:47], v[156:159], v[96:99], v[32:47]
	ds_read_b64_tr_b16 v[178:179], v221 offset:14848
	ds_read_b64_tr_b16 v[180:181], v221 offset:15872
	v_add_f32_e32 v129, v146, v129
	v_add_f32_e32 v131, v147, v131
	v_cvt_pk_bf16_f32 v132, v132, v133
	v_cvt_pk_bf16_f32 v133, v134, v135
	v_cvt_pk_bf16_f32 v134, v136, v137
	v_cvt_pk_bf16_f32 v135, v138, v139
	v_cvt_pk_bf16_f32 v136, v140, v141
	s_waitcnt lgkmcnt(4)
	v_mfma_f32_32x32x16_bf16 v[0:15], v[162:165], v[96:99], v[0:15]
	v_cvt_pk_bf16_f32 v137, v142, v143
	v_cvt_pk_bf16_f32 v138, v144, v145
	v_cvt_pk_bf16_f32 v139, v146, v147
	v_exp_f32_e32 v184, v184
	v_exp_f32_e32 v185, v185
	v_exp_f32_e32 v186, v186
	s_waitcnt lgkmcnt(2)
	v_mfma_f32_32x32x16_bf16 v[32:47], v[174:177], v[100:103], v[32:47]
	v_exp_f32_e32 v187, v187
	v_exp_f32_e32 v188, v188
	v_exp_f32_e32 v189, v189
	v_exp_f32_e32 v190, v190
	v_exp_f32_e32 v191, v191
	v_exp_f32_e32 v192, v192
	v_exp_f32_e32 v193, v193
	s_waitcnt lgkmcnt(0)
	v_mfma_f32_32x32x16_bf16 v[0:15], v[178:181], v[100:103], v[0:15]
	v_exp_f32_e32 v194, v194
	v_exp_f32_e32 v195, v195
	v_exp_f32_e32 v196, v196
	v_exp_f32_e32 v197, v197
	v_exp_f32_e32 v198, v198
	v_exp_f32_e32 v199, v199
	s_waitcnt lgkmcnt(10)
	v_mfma_f32_32x32x16_bf16 v[64:79], v[112:115], v[80:83], 0
	v_add_f32_e32 v129, v184, v129
	v_add_f32_e32 v131, v185, v131
	v_add_f32_e32 v129, v186, v129
	v_add_f32_e32 v131, v187, v131
	v_add_f32_e32 v129, v188, v129
	v_add_f32_e32 v131, v189, v131
	v_add_f32_e32 v129, v190, v129
	v_mfma_f32_32x32x16_bf16 v[96:111], v[116:119], v[80:83], 0
	v_add_f32_e32 v131, v191, v131
	v_add_f32_e32 v129, v192, v129
	v_add_f32_e32 v131, v193, v131
	v_add_f32_e32 v129, v194, v129
	v_add_f32_e32 v131, v195, v131
	v_add_f32_e32 v129, v196, v129
	v_mfma_f32_32x32x16_bf16 v[64:79], v[148:151], v[84:87], v[64:79]
	v_add_f32_e32 v131, v197, v131
	v_add_f32_e32 v129, v198, v129
	v_add_f32_e32 v131, v199, v131
	v_cvt_pk_bf16_f32 v184, v184, v185
	v_cvt_pk_bf16_f32 v185, v186, v187
	v_cvt_pk_bf16_f32 v186, v188, v189
	v_cvt_pk_bf16_f32 v187, v190, v191
	v_mfma_f32_32x32x16_bf16 v[96:111], v[152:155], v[84:87], v[96:111]
	v_cvt_pk_bf16_f32 v188, v192, v193
	v_cvt_pk_bf16_f32 v189, v194, v195
	v_cvt_pk_bf16_f32 v190, v196, v197
	v_cvt_pk_bf16_f32 v191, v198, v199
	v_add_u32_e32 v219, s20, v202
	v_add_u32_e32 v220, s20, v203
	ds_read_b64_tr_b16 v[156:157], v221 offset:8192
	ds_read_b64_tr_b16 v[158:159], v221 offset:9216
	ds_read_b64_tr_b16 v[162:163], v221 offset:8704
	ds_read_b64_tr_b16 v[164:165], v221 offset:9728
	ds_read_b64_tr_b16 v[174:175], v221 offset:10240
	ds_read_b64_tr_b16 v[176:177], v221 offset:11264
	ds_read_b128 v[112:115], v219
	ds_read_b128 v[116:119], v219 offset:4096
	ds_read_b128 v[148:151], v220
	ds_read_b128 v[152:155], v220 offset:4096
	v_exp_f32_e32 v64, v64
	v_exp_f32_e32 v65, v65
	v_exp_f32_e32 v66, v66
	v_exp_f32_e32 v67, v67
	s_waitcnt lgkmcnt(8)
	v_mfma_f32_32x32x16_bf16 v[48:63], v[156:159], v[132:135], v[48:63]
	ds_read_b64_tr_b16 v[178:179], v221 offset:10752
	ds_read_b64_tr_b16 v[180:181], v221 offset:11776
	v_exp_f32_e32 v68, v68
	v_exp_f32_e32 v69, v69
	v_exp_f32_e32 v70, v70
	v_exp_f32_e32 v71, v71
	v_exp_f32_e32 v72, v72
	v_exp_f32_e32 v73, v73
	v_exp_f32_e32 v74, v74
	s_waitcnt lgkmcnt(8)
	v_mfma_f32_32x32x16_bf16 v[16:31], v[162:165], v[132:135], v[16:31]
	ds_read_b64_tr_b16 v[156:157], v221 offset:12288
	ds_read_b64_tr_b16 v[158:159], v221 offset:13312
	v_exp_f32_e32 v75, v75
	v_exp_f32_e32 v76, v76
	v_exp_f32_e32 v77, v77
	v_exp_f32_e32 v78, v78
	v_exp_f32_e32 v79, v79
	v_add_f32_e32 v128, v64, v128
	s_waitcnt lgkmcnt(8)
	v_mfma_f32_32x32x16_bf16 v[48:63], v[174:177], v[136:139], v[48:63]
	ds_read_b64_tr_b16 v[162:163], v221 offset:12800
	ds_read_b64_tr_b16 v[164:165], v221 offset:13824
	v_add_f32_e32 v130, v65, v130
	v_add_f32_e32 v128, v66, v128
	v_add_f32_e32 v130, v67, v130
	v_add_f32_e32 v128, v68, v128
	v_add_f32_e32 v130, v69, v130
	v_add_f32_e32 v128, v70, v128
	v_add_f32_e32 v130, v71, v130
	s_waitcnt lgkmcnt(4)
	v_mfma_f32_32x32x16_bf16 v[16:31], v[178:181], v[136:139], v[16:31]
	ds_read_b64_tr_b16 v[174:175], v221 offset:14336
	ds_read_b64_tr_b16 v[176:177], v221 offset:15360
	v_add_f32_e32 v128, v72, v128
	v_add_f32_e32 v130, v73, v130
	v_add_f32_e32 v128, v74, v128
	v_add_f32_e32 v130, v75, v130
	v_add_f32_e32 v128, v76, v128
	v_add_f32_e32 v130, v77, v130
	s_waitcnt lgkmcnt(4)
	v_mfma_f32_32x32x16_bf16 v[48:63], v[156:159], v[184:187], v[48:63]
	ds_read_b64_tr_b16 v[178:179], v221 offset:14848
	ds_read_b64_tr_b16 v[180:181], v221 offset:15872
	v_add_f32_e32 v128, v78, v128
	v_add_f32_e32 v130, v79, v130
	v_cvt_pk_bf16_f32 v64, v64, v65
	v_cvt_pk_bf16_f32 v65, v66, v67
	v_cvt_pk_bf16_f32 v66, v68, v69
	v_cvt_pk_bf16_f32 v67, v70, v71
	v_cvt_pk_bf16_f32 v68, v72, v73
	s_waitcnt lgkmcnt(4)
	v_mfma_f32_32x32x16_bf16 v[16:31], v[162:165], v[184:187], v[16:31]
	v_cvt_pk_bf16_f32 v69, v74, v75
	v_cvt_pk_bf16_f32 v70, v76, v77
	v_cvt_pk_bf16_f32 v71, v78, v79
	v_exp_f32_e32 v96, v96
	v_exp_f32_e32 v97, v97
	v_exp_f32_e32 v98, v98
	s_waitcnt lgkmcnt(2)
	v_mfma_f32_32x32x16_bf16 v[48:63], v[174:177], v[188:191], v[48:63]
	v_exp_f32_e32 v99, v99
	v_exp_f32_e32 v100, v100
	v_exp_f32_e32 v101, v101
	v_exp_f32_e32 v102, v102
	v_exp_f32_e32 v103, v103
	v_exp_f32_e32 v104, v104
	v_exp_f32_e32 v105, v105
	s_waitcnt lgkmcnt(0)
	v_mfma_f32_32x32x16_bf16 v[16:31], v[178:181], v[188:191], v[16:31]
	v_exp_f32_e32 v106, v106
	v_exp_f32_e32 v107, v107
	v_exp_f32_e32 v108, v108
	v_exp_f32_e32 v109, v109
	v_exp_f32_e32 v110, v110
	v_exp_f32_e32 v111, v111
	s_waitcnt lgkmcnt(10)
	v_mfma_f32_32x32x16_bf16 v[132:147], v[112:115], v[88:91], 0
	v_add_f32_e32 v128, v96, v128
	v_add_f32_e32 v130, v97, v130
	v_add_f32_e32 v128, v98, v128
	v_add_f32_e32 v130, v99, v130
	v_add_f32_e32 v128, v100, v128
	v_add_f32_e32 v130, v101, v130
	v_add_f32_e32 v128, v102, v128
	v_mfma_f32_32x32x16_bf16 v[184:199], v[116:119], v[88:91], 0
	v_add_f32_e32 v130, v103, v130
	v_add_f32_e32 v128, v104, v128
	v_add_f32_e32 v130, v105, v130
	v_add_f32_e32 v128, v106, v128
	v_add_f32_e32 v130, v107, v130
	v_add_f32_e32 v128, v108, v128
	v_mfma_f32_32x32x16_bf16 v[132:147], v[148:151], v[92:95], v[132:147]
	v_add_f32_e32 v130, v109, v130
	v_add_f32_e32 v128, v110, v128
	v_add_f32_e32 v130, v111, v130
	v_cvt_pk_bf16_f32 v96, v96, v97
	v_cvt_pk_bf16_f32 v97, v98, v99
	v_cvt_pk_bf16_f32 v98, v100, v101
	v_cvt_pk_bf16_f32 v99, v102, v103
	v_mfma_f32_32x32x16_bf16 v[184:199], v[152:155], v[92:95], v[184:199]
	v_cvt_pk_bf16_f32 v100, v104, v105
	v_cvt_pk_bf16_f32 v101, v106, v107
	v_cvt_pk_bf16_f32 v102, v108, v109
	v_cvt_pk_bf16_f32 v103, v110, v111
	s_cmpk_lt_u32 s15, 0x81
	s_cbranch_scc0 .Ldiff_w0
	s_waitcnt vmcnt(2)
	s_branch .Ldiff_w1

.Ldiff_w1:
	s_barrier
	s_add_i32 s15, s15, 1
	s_add_i32 s17, s17, 64
	s_cmpk_lt_u32 s15, 0x83
	s_cbranch_scc1 .Ldiff_loop
	s_and_b32 s19, s15, 3
	s_lshl_b32 s19, s19, 14
	v_add_u32_e32 v221, s19, v204
	ds_read_b64_tr_b16 v[156:157], v221 offset:8192
	ds_read_b64_tr_b16 v[158:159], v221 offset:9216
	ds_read_b64_tr_b16 v[162:163], v221 offset:8704
	ds_read_b64_tr_b16 v[164:165], v221 offset:9728
	ds_read_b64_tr_b16 v[174:175], v221 offset:10240
	ds_read_b64_tr_b16 v[176:177], v221 offset:11264
	v_exp_f32_e32 v132, v132
	v_exp_f32_e32 v133, v133
	v_exp_f32_e32 v134, v134
	v_exp_f32_e32 v135, v135
	s_waitcnt lgkmcnt(4)
	v_mfma_f32_32x32x16_bf16 v[32:47], v[156:159], v[64:67], v[32:47]
	ds_read_b64_tr_b16 v[178:179], v221 offset:10752
	ds_read_b64_tr_b16 v[180:181], v221 offset:11776
	v_exp_f32_e32 v136, v136
	v_exp_f32_e32 v137, v137
	v_exp_f32_e32 v138, v138
	v_exp_f32_e32 v139, v139
	v_exp_f32_e32 v140, v140
	v_exp_f32_e32 v141, v141
	v_exp_f32_e32 v142, v142
	v_exp_f32_e32 v143, v143
	v_exp_f32_e32 v144, v144
	v_exp_f32_e32 v145, v145
	s_waitcnt lgkmcnt(4)
	v_mfma_f32_32x32x16_bf16 v[0:15], v[162:165], v[64:67], v[0:15]
	ds_read_b64_tr_b16 v[156:157], v221 offset:12288
	ds_read_b64_tr_b16 v[158:159], v221 offset:13312
	v_exp_f32_e32 v146, v146
	v_exp_f32_e32 v147, v147
	v_add_f32_e32 v129, v132, v129
	v_add_f32_e32 v131, v133, v131
	v_add_f32_e32 v129, v134, v129
	v_add_f32_e32 v131, v135, v131
	v_add_f32_e32 v129, v136, v129
	v_add_f32_e32 v131, v137, v131
	v_add_f32_e32 v129, v138, v129
	v_add_f32_e32 v131, v139, v131
	v_add_f32_e32 v129, v140, v129
	s_waitcnt lgkmcnt(4)
	v_mfma_f32_32x32x16_bf16 v[32:47], v[174:177], v[68:71], v[32:47]
	ds_read_b64_tr_b16 v[162:163], v221 offset:12800
	ds_read_b64_tr_b16 v[164:165], v221 offset:13824
	v_add_f32_e32 v131, v141, v131
	v_add_f32_e32 v129, v142, v129
	v_add_f32_e32 v131, v143, v131
	v_add_f32_e32 v129, v144, v129
	v_add_f32_e32 v131, v145, v131
	v_add_f32_e32 v129, v146, v129
	v_add_f32_e32 v131, v147, v131
	v_cvt_pk_bf16_f32 v132, v132, v133
	v_cvt_pk_bf16_f32 v133, v134, v135
	v_cvt_pk_bf16_f32 v134, v136, v137
	s_waitcnt lgkmcnt(4)
	v_mfma_f32_32x32x16_bf16 v[0:15], v[178:181], v[68:71], v[0:15]
	ds_read_b64_tr_b16 v[174:175], v221 offset:14336
	ds_read_b64_tr_b16 v[176:177], v221 offset:15360
	v_cvt_pk_bf16_f32 v135, v138, v139
	v_cvt_pk_bf16_f32 v136, v140, v141
	v_cvt_pk_bf16_f32 v137, v142, v143
	v_cvt_pk_bf16_f32 v138, v144, v145
	v_cvt_pk_bf16_f32 v139, v146, v147
	v_exp_f32_e32 v184, v184
	v_exp_f32_e32 v185, v185
	v_exp_f32_e32 v186, v186
	v_exp_f32_e32 v187, v187
	v_exp_f32_e32 v188, v188
	s_waitcnt lgkmcnt(4)
	v_mfma_f32_32x32x16_bf16 v[32:47], v[156:159], v[96:99], v[32:47]
	ds_read_b64_tr_b16 v[178:179], v221 offset:14848
	ds_read_b64_tr_b16 v[180:181], v221 offset:15872
	v_exp_f32_e32 v189, v189
	v_exp_f32_e32 v190, v190
	v_exp_f32_e32 v191, v191
	v_exp_f32_e32 v192, v192
	v_exp_f32_e32 v193, v193
	v_exp_f32_e32 v194, v194
	v_exp_f32_e32 v195, v195
	v_exp_f32_e32 v196, v196
	v_exp_f32_e32 v197, v197
	v_exp_f32_e32 v198, v198
	s_waitcnt lgkmcnt(4)
	v_mfma_f32_32x32x16_bf16 v[0:15], v[162:165], v[96:99], v[0:15]
	v_exp_f32_e32 v199, v199
	v_add_f32_e32 v129, v184, v129
	v_add_f32_e32 v131, v185, v131
	v_add_f32_e32 v129, v186, v129
	v_add_f32_e32 v131, v187, v131
	v_add_f32_e32 v129, v188, v129
	v_add_f32_e32 v131, v189, v131
	v_add_f32_e32 v129, v190, v129
	v_add_f32_e32 v131, v191, v131
	v_add_f32_e32 v129, v192, v129
	v_add_f32_e32 v131, v193, v131
	s_waitcnt lgkmcnt(2)
	v_mfma_f32_32x32x16_bf16 v[32:47], v[174:177], v[100:103], v[32:47]
	v_add_f32_e32 v129, v194, v129
	v_add_f32_e32 v131, v195, v131
	v_add_f32_e32 v129, v196, v129
	v_add_f32_e32 v131, v197, v131
	v_add_f32_e32 v129, v198, v129
	v_add_f32_e32 v131, v199, v131
	v_cvt_pk_bf16_f32 v184, v184, v185
	v_cvt_pk_bf16_f32 v185, v186, v187
	v_cvt_pk_bf16_f32 v186, v188, v189
	v_cvt_pk_bf16_f32 v187, v190, v191
	s_waitcnt lgkmcnt(0)
	v_mfma_f32_32x32x16_bf16 v[0:15], v[178:181], v[100:103], v[0:15]
	v_cvt_pk_bf16_f32 v188, v192, v193
	v_cvt_pk_bf16_f32 v189, v194, v195
	v_cvt_pk_bf16_f32 v190, v196, v197
	v_cvt_pk_bf16_f32 v191, v198, v199
	ds_read_b64_tr_b16 v[156:157], v221 offset:8192
	ds_read_b64_tr_b16 v[158:159], v221 offset:9216
	ds_read_b64_tr_b16 v[162:163], v221 offset:8704
	ds_read_b64_tr_b16 v[164:165], v221 offset:9728
	ds_read_b64_tr_b16 v[174:175], v221 offset:10240
	ds_read_b64_tr_b16 v[176:177], v221 offset:11264
	s_waitcnt lgkmcnt(4)
	v_mfma_f32_32x32x16_bf16 v[48:63], v[156:159], v[132:135], v[48:63]
	ds_read_b64_tr_b16 v[178:179], v221 offset:10752
	ds_read_b64_tr_b16 v[180:181], v221 offset:11776
	s_waitcnt lgkmcnt(4)
	v_mfma_f32_32x32x16_bf16 v[16:31], v[162:165], v[132:135], v[16:31]
	ds_read_b64_tr_b16 v[156:157], v221 offset:12288
	ds_read_b64_tr_b16 v[158:159], v221 offset:13312
	s_waitcnt lgkmcnt(4)
	v_mfma_f32_32x32x16_bf16 v[48:63], v[174:177], v[136:139], v[48:63]
	ds_read_b64_tr_b16 v[162:163], v221 offset:12800
	ds_read_b64_tr_b16 v[164:165], v221 offset:13824
	s_waitcnt lgkmcnt(4)
	v_mfma_f32_32x32x16_bf16 v[16:31], v[178:181], v[136:139], v[16:31]
	ds_read_b64_tr_b16 v[174:175], v221 offset:14336
	ds_read_b64_tr_b16 v[176:177], v221 offset:15360
	s_waitcnt lgkmcnt(4)
	v_mfma_f32_32x32x16_bf16 v[48:63], v[156:159], v[184:187], v[48:63]
	ds_read_b64_tr_b16 v[178:179], v221 offset:14848
	ds_read_b64_tr_b16 v[180:181], v221 offset:15872
	s_waitcnt lgkmcnt(4)
	v_mfma_f32_32x32x16_bf16 v[16:31], v[162:165], v[184:187], v[16:31]
	s_waitcnt lgkmcnt(2)
	v_mfma_f32_32x32x16_bf16 v[48:63], v[174:177], v[188:191], v[48:63]
	s_waitcnt lgkmcnt(0)
	v_mfma_f32_32x32x16_bf16 v[16:31], v[178:181], v[188:191], v[16:31]
	s_barrier
	v_add_f32_e32 v128, v128, v130
	v_add_f32_e32 v129, v129, v131
	s_branch .LBB0_561
